# up GEMM -> down-projection GEMM without the grid barrier: per-(row tile, K half) counters plus a weight-converter counter; the consumer's wave 0 waits, invalidates once
# speedup vs baseline: 1.0047x; 1.0047x over previous
.LBB0_461:
	s_waitcnt vmcnt(0)
	s_waitcnt vmcnt(0) lgkmcnt(0)
	s_barrier
	s_and_saveexec_b64 s[4:5], s[8:9]
	v_readlane_b32 s0, v255, 0
	s_nop 3
	s_and_b32 s1, s0, 7
	s_lshr_b32 s2, s0, 3
	s_mul_i32 s3, s1, 88
	s_add_i32 s3, s3, s2
	s_add_u32 s14, s6, 0xe800000
	s_addc_u32 s15, s7, 0
	v_mov_b32_e32 v0, 1
	s_add_i32 s8, s3, 0
	s_mul_i32 s9, s8, 0x5d18
	s_lshr_b32 s9, s9, 22
	s_mul_i32 s10, s9, 0xb0
	s_sub_i32 s10, s8, s10
	s_and_b32 s11, s10, 7
	s_lshl_b32 s9, s9, 3
	s_add_i32 s9, s9, s11
	s_lshr_b32 s10, s10, 3
	s_cmp_ge_u32 s10, 11
	s_cselect_b32 s10, 1, 0
	s_lshl_b32 s9, s9, 1
	s_add_i32 s9, s9, s10
	s_lshl_b32 s9, s9, 6
	s_add_i32 s9, s9, 0x2400
	v_mov_b32_e32 v2, s9
	global_atomic_add v2, v0, s[14:15]
	s_add_i32 s8, s3, 32
	s_mul_i32 s9, s8, 0x5d18
	s_lshr_b32 s9, s9, 22
	s_mul_i32 s10, s9, 0xb0
	s_sub_i32 s10, s8, s10
	s_and_b32 s11, s10, 7
	s_lshl_b32 s9, s9, 3
	s_add_i32 s9, s9, s11
	s_lshr_b32 s10, s10, 3
	s_cmp_ge_u32 s10, 11
	s_cselect_b32 s10, 1, 0
	s_lshl_b32 s9, s9, 1
	s_add_i32 s9, s9, s10
	s_lshl_b32 s9, s9, 6
	s_add_i32 s9, s9, 0x2400
	v_mov_b32_e32 v2, s9
	global_atomic_add v2, v0, s[14:15]
	s_cmp_ge_u32 s0, 0xc0
	s_cbranch_scc1 .Luf_conv
	s_add_i32 s8, s3, 64
	s_mul_i32 s9, s8, 0x5d18
	s_lshr_b32 s9, s9, 22
	s_mul_i32 s10, s9, 0xb0
	s_sub_i32 s10, s8, s10
	s_and_b32 s11, s10, 7
	s_lshl_b32 s9, s9, 3
	s_add_i32 s9, s9, s11
	s_lshr_b32 s10, s10, 3
	s_cmp_ge_u32 s10, 11
	s_cselect_b32 s10, 1, 0
	s_lshl_b32 s9, s9, 1
	s_add_i32 s9, s9, s10
	s_lshl_b32 s9, s9, 6
	s_add_i32 s9, s9, 0x2400
	v_mov_b32_e32 v2, s9
	global_atomic_add v2, v0, s[14:15]
	s_branch .Luf_sigd
.Luf_conv:
	v_mov_b32_e32 v2, 0
	global_atomic_add v2, v0, s[14:15]
.Luf_sigd:
	v_mov_b32_e32 v2, 0x20174
	ds_add_u32 v2, v0
.LBB0_514:
	s_or_b64 exec, exec, s[4:5]
	s_mov_b64 s[4:5], s[66:67]
	v_mov_b32_e32 v0, v1
	s_waitcnt lgkmcnt(0)
	s_barrier
	s_cmp_lg_u32 s86, 0
	s_cbranch_scc1 .Luf_done
	s_load_dwordx2 s[6:7], s[66:67], 0x100
	v_mov_b32_e32 v2, 0x20174
	ds_read_b32 v3, v2
	v_readlane_b32 s0, v255, 0
	s_nop 3
	s_and_b32 s1, s0, 7
	s_lshl_b32 s1, s1, 5
	s_lshr_b32 s0, s0, 3
	s_add_i32 s0, s0, s1
	s_lshr_b32 s1, s0, 6
	s_lshl_b32 s1, s1, 3
	s_and_b32 s2, s0, 7
	s_add_i32 s1, s1, s2
	s_bfe_u32 s2, s0, 0x10005
	s_lshl_b32 s1, s1, 1
	s_add_i32 s1, s1, s2
	s_lshl_b32 s1, s1, 6
	s_add_i32 s1, s1, 0x2400
	v_mov_b32_e32 v4, s1
	v_mov_b32_e32 v5, 0
	s_waitcnt lgkmcnt(0)
	s_add_u32 s6, s6, 0xe800000
	s_addc_u32 s7, s7, 0
	v_mul_u32_u24_e32 v6, 11, v3
	v_lshlrev_b32_e32 v7, 6, v3
.Luf_loop:
	global_load_dword v8, v4, s[6:7] sc1
	global_load_dword v9, v5, s[6:7] sc1
	s_waitcnt vmcnt(0)
	v_cmp_le_u32_e32 vcc, v6, v8
	s_nop 1
	s_andn2_b64 s[0:1], exec, vcc
	s_cbranch_scc1 .Luf_sleep
	v_cmp_le_u32_e32 vcc, v7, v9
	s_cbranch_vccz .Luf_sleep
	s_branch .Luf_rel

.Luf_done:
	s_barrier
	v_readlane_b32 s0, v254, 27
	v_mbcnt_lo_u32_b32 v0, -1, v0
	v_mbcnt_hi_u32_b32 v18, -1, v0
	v_add_u32_e32 v0, s86, v18
	v_readlane_b32 s1, v254, 28
	s_andn2_b64 vcc, exec, s[0:1]
	v_readfirstlane_b32 s6, v0
	s_cbranch_vccnz .LBB0_538
	v_lshlrev_b32_e32 v2, 4, v0
	v_add_u32_e32 v3, 0x2000, v2
	v_ashrrev_i32_e32 v4, 31, v3
	v_lshrrev_b32_e32 v4, 22, v4
	v_add_u32_e32 v4, v3, v4
	v_ashrrev_i32_e32 v10, 10, v4
	v_mul_i32_i24_e32 v4, 0x400, v10
	v_sub_u32_e32 v3, v3, v4
	v_lshrrev_b32_e32 v4, 4, v3
	v_bitop3_b32 v3, v4, v3, 32 bitop3:0x6c
	v_ashrrev_i32_e32 v4, 31, v3
	v_lshrrev_b32_e32 v4, 26, v4
	v_add_u32_e32 v4, v3, v4
	v_lshlrev_b32_e32 v5, 3, v10
	v_ashrrev_i32_e32 v11, 6, v4
	v_and_b32_e32 v5, -16, v5
	v_add_u32_e32 v5, v11, v5
	v_and_b32_e32 v6, 3, v11
	s_mov_b32 s9, 0xffffe0
	v_lshrrev_b32_e32 v7, 2, v5
	v_lshlrev_b32_e32 v8, 1, v5
	v_and_b32_e32 v4, 0xc0, v4
	v_and_or_b32 v6, v5, s9, v6
	v_and_b32_e32 v7, 4, v7
	v_and_b32_e32 v8, 24, v8
	v_sub_u32_e32 v3, v3, v4
	v_or3_b32 v6, v6, v7, v8
	v_lshlrev_b32_e32 v7, 5, v10
	v_ashrrev_i16_sdwa v3, v236, sext(v3) dst_sel:DWORD dst_unused:UNUSED_PAD src0_sel:DWORD src1_sel:BYTE_0
	v_and_b32_e32 v12, 32, v7
	v_bfe_i32 v13, v3, 0, 16
	s_movk_i32 s8, 0xb00
	v_mul_u32_u24_e32 v6, 0xb00, v6
	v_add_u32_e32 v3, v12, v13
	v_mul_lo_u32 v4, v5, s8
	v_add_lshl_u32 v130, v6, v3, 1
	v_add_lshl_u32 v132, v3, v4, 1
	v_bfe_i32 v3, v0, 27, 1
	s_load_dwordx2 s[4:5], s[4:5], 0x100
	v_lshrrev_b32_e32 v3, 22, v3
	v_add_u32_e32 v3, v2, v3
	v_and_b32_e32 v3, 0xfffffc00, v3
	v_sub_u32_e32 v2, v2, v3
	v_lshrrev_b32_e32 v3, 4, v2
	v_ashrrev_i32_e32 v4, 31, v0
	s_waitcnt lgkmcnt(0)
	s_add_u32 s0, s4, 0x6c00000
	v_bitop3_b32 v2, v3, v2, 32 bitop3:0x6c
	v_lshrrev_b32_e32 v4, 26, v4
	s_mul_hi_u32 s2, s52, 0x580000
	s_mul_i32 s52, s52, 0x580000
	s_addc_u32 s1, s5, 0
	v_ashrrev_i32_e32 v3, 31, v2
	v_add_u32_e32 v0, v0, v4
	s_add_u32 s3, s4, s52
	v_lshrrev_b32_e32 v3, 26, v3
	v_ashrrev_i32_e32 v15, 6, v0
	s_addc_u32 s7, s5, s2
	v_add_u32_e32 v3, v2, v3
	v_lshlrev_b32_e32 v0, 3, v15
	s_add_u32 s2, s3, 0x2c00000
	v_ashrrev_i32_e32 v14, 6, v3
	v_and_b32_e32 v0, -16, v0
	s_addc_u32 s3, s7, 0
	s_ashr_i32 s7, s6, 6
	v_add_u32_e32 v4, v14, v0
	v_and_b32_e32 v3, 0xc0, v3
	s_ashr_i32 s10, s6, 8
	s_lshl_b32 s22, s7, 10
	v_and_b32_e32 v0, 3, v14
	v_lshrrev_b32_e32 v5, 2, v4
	v_lshlrev_b32_e32 v6, 1, v4
	v_sub_u32_e32 v2, v2, v3
	v_mul_lo_u32 v3, v4, s8
	v_readlane_b32 s8, v254, 39
	v_and_or_b32 v0, v4, s9, v0
	v_and_b32_e32 v5, 4, v5
	v_and_b32_e32 v6, 24, v6
	s_add_u32 s8, s2, s8
	v_readlane_b32 s9, v254, 38
	v_or3_b32 v0, v0, v5, v6
	v_lshlrev_b32_e32 v5, 5, v15
	v_ashrrev_i16_sdwa v2, v236, sext(v2) dst_sel:DWORD dst_unused:UNUSED_PAD src0_sel:DWORD src1_sel:BYTE_0
	s_addc_u32 s9, s3, s9
	v_readlane_b32 s14, v254, 37
	v_and_b32_e32 v16, 32, v5
	v_bfe_i32 v17, v2, 0, 16
	s_add_u32 s16, s8, s14
	v_readlane_b32 s13, v254, 36
	v_mul_u32_u24_e32 v0, 0xb00, v0
	v_add_u32_e32 v2, v16, v17
	s_addc_u32 s17, s9, s13
	s_add_i32 s23, s22, 0
	v_add_lshl_u32 v0, v0, v2, 1
	s_add_i32 m0, s23, 0x10000
	v_readlane_b32 s8, v254, 56
	global_load_lds_dwordx4 v0, s[16:17]
	s_add_i32 m0, s23, 0x12000
	s_mov_b32 s12, s8
	s_mul_i32 s8, s8, 0x160000
	s_add_u32 s11, s0, s8
	s_mul_hi_i32 s8, s12, 0x160000
	s_addc_u32 s12, s1, s8
	v_readlane_b32 s9, v254, 57
	s_add_u32 s8, s16, 0xb0000
	global_load_lds_dwordx4 v130, s[16:17]
	s_addc_u32 s9, s17, 0
	s_add_i32 m0, s23, 0x14000
	v_add_lshl_u32 v134, v2, v3, 1
	global_load_lds_dwordx4 v0, s[8:9]
	s_add_i32 m0, s23, 0x16000
	s_add_u32 s14, s11, s14
	s_addc_u32 s15, s12, s13
	s_add_i32 s24, s23, 0x2000
	global_load_lds_dwordx4 v130, s[8:9]
	s_mov_b32 m0, s23
	s_add_u32 s8, s14, 0xb0000
	global_load_lds_dwordx4 v134, s[14:15]
	s_mov_b32 m0, s24
	s_addc_u32 s9, s15, 0
	s_add_i32 s25, s23, 0x4000
	global_load_lds_dwordx4 v132, s[14:15]
	s_mov_b32 m0, s25
	s_add_i32 s26, s23, 0x6000
	global_load_lds_dwordx4 v134, s[8:9]
	s_mov_b32 m0, s26
	v_mov_b32_e32 v131, v1
	global_load_lds_dwordx4 v132, s[8:9]
	v_mov_b32_e32 v135, v1
	v_mov_b32_e32 v133, v1
	s_cmp_eq_u32 s10, 1
	v_lshl_add_u64 v[8:9], s[16:17], 0, v[0:1]
	v_lshl_add_u64 v[6:7], s[16:17], 0, v[130:131]
	v_lshl_add_u64 v[2:3], s[14:15], 0, v[134:135]
	s_cselect_b64 s[8:9], -1, 0
	s_cmp_lg_u32 s10, 1
	v_lshl_add_u64 v[4:5], s[14:15], 0, v[132:133]
	s_cbranch_scc1 .LBB0_517
	s_barrier
